# speedup vs baseline: 1.0010x; 1.0010x over previous
.LBB0_413:
	v_add_u32_e32 v242, s27, v234
	ds_read_b64_tr_b16 v[160:161], v242 offset:0x0
	ds_read_b64_tr_b16 v[162:163], v242 offset:0x100
	ds_read_b64_tr_b16 v[164:165], v242 offset:0x1000
	ds_read_b64_tr_b16 v[166:167], v242 offset:0x1100
	s_waitcnt lgkmcnt(2)
	v_mfma_f32_32x32x16_bf16 v[128:143], v[216:219], v[160:163], v[128:143]
	ds_read_b64_tr_b16 v[168:169], v242 offset:0x200
	v_mfma_f32_32x32x16_bf16 v[96:111], v[212:215], v[160:163], v[96:111]
	ds_read_b64_tr_b16 v[170:171], v242 offset:0x300
	s_waitcnt lgkmcnt(2)
	v_mfma_f32_32x32x16_bf16 v[128:143], v[224:227], v[164:167], v[128:143]
	ds_read_b64_tr_b16 v[172:173], v242 offset:0x1200
	v_mfma_f32_32x32x16_bf16 v[96:111], v[220:223], v[164:167], v[96:111]
	ds_read_b64_tr_b16 v[174:175], v242 offset:0x1300
	s_waitcnt lgkmcnt(2)
	v_mfma_f32_32x32x16_bf16 v[112:127], v[216:219], v[168:171], v[112:127]
	ds_read_b64_tr_b16 v[160:161], v242 offset:0x400
	v_mfma_f32_32x32x16_bf16 v[80:95], v[212:215], v[168:171], v[80:95]
	ds_read_b64_tr_b16 v[162:163], v242 offset:0x500
	s_waitcnt lgkmcnt(2)
	v_mfma_f32_32x32x16_bf16 v[112:127], v[224:227], v[172:175], v[112:127]
	ds_read_b64_tr_b16 v[164:165], v242 offset:0x1400
	v_mfma_f32_32x32x16_bf16 v[80:95], v[220:223], v[172:175], v[80:95]
	ds_read_b64_tr_b16 v[166:167], v242 offset:0x1500
	ds_read_b128 v[144:147], v241 offset:0x2000
	ds_read_b128 v[148:151], v240 offset:0x2000
	ds_read_b128 v[152:155], v239 offset:0x2000
	ds_read_b128 v[156:159], v0 offset:0x2000
	s_waitcnt lgkmcnt(6)
	v_mfma_f32_32x32x16_bf16 v[64:79], v[216:219], v[160:163], v[64:79]
	ds_read_b64_tr_b16 v[168:169], v242 offset:0x600
	v_mfma_f32_32x32x16_bf16 v[32:47], v[212:215], v[160:163], v[32:47]
	ds_read_b64_tr_b16 v[170:171], v242 offset:0x700
	s_waitcnt lgkmcnt(6)
	v_mfma_f32_32x32x16_bf16 v[64:79], v[224:227], v[164:167], v[64:79]
	ds_read_b64_tr_b16 v[172:173], v242 offset:0x1600
	v_mfma_f32_32x32x16_bf16 v[32:47], v[220:223], v[164:167], v[32:47]
	ds_read_b64_tr_b16 v[174:175], v242 offset:0x1700
	s_waitcnt lgkmcnt(2)
	v_mfma_f32_32x32x16_bf16 v[48:63], v[216:219], v[168:171], v[48:63]
	v_mfma_f32_32x32x16_bf16 v[16:31], v[212:215], v[168:171], v[16:31]
	s_waitcnt lgkmcnt(0)
	v_mfma_f32_32x32x16_bf16 v[48:63], v[224:227], v[172:175], v[48:63]
	v_mfma_f32_32x32x16_bf16 v[16:31], v[220:223], v[172:175], v[16:31]
	s_waitcnt lgkmcnt(0)
	s_barrier
	v_mfma_f32_32x32x16_bf16 v[212:227], v[144:147], v[176:179], 0
	v_mfma_f32_32x32x16_bf16 v[212:227], v[148:151], v[180:183], v[212:227]
	v_mfma_f32_32x32x16_bf16 v[212:227], v[152:155], v[184:187], v[212:227]
	v_mfma_f32_32x32x16_bf16 v[212:227], v[156:159], v[188:191], v[212:227]
	ds_read_b128 v[144:147], v241 offset:0x2080
	ds_read_b128 v[148:151], v240 offset:0x2080
	ds_read_b128 v[152:155], v239 offset:0x2080
	ds_read_b128 v[156:159], v0 offset:0x2080
	v_cmp_eq_f32_e32 vcc, 0, v238
	v_cmp_eq_f32_e64 s[10:11], 0, v237
	s_and_b64 s[0:1], vcc, s[10:11]
	s_cmp_eq_u64 s[0:1], exec
	s_waitcnt lgkmcnt(0)
	v_mfma_f32_32x32x16_bf16 v[160:175], v[144:147], v[192:195], 0
	v_mfma_f32_32x32x16_bf16 v[160:175], v[148:151], v[196:199], v[160:175]
	v_mfma_f32_32x32x16_bf16 v[160:175], v[152:155], v[200:203], v[160:175]
	v_mfma_f32_32x32x16_bf16 v[160:175], v[156:159], v[204:207], v[160:175]
	s_cbranch_scc0 .Lfz2o_c0
	v_exp_f32_e32 v144, v212
	v_exp_f32_e32 v145, v213
	v_exp_f32_e32 v146, v214
	v_exp_f32_e32 v147, v215
	v_exp_f32_e32 v148, v216
	v_exp_f32_e32 v149, v217
	v_exp_f32_e32 v150, v218
	v_exp_f32_e32 v151, v219
	v_exp_f32_e32 v152, v220
	v_exp_f32_e32 v153, v221
	v_exp_f32_e32 v154, v222
	v_exp_f32_e32 v155, v223
	v_exp_f32_e32 v156, v224
	v_exp_f32_e32 v157, v225
	v_exp_f32_e32 v158, v226
	v_exp_f32_e32 v159, v227
	v_add_f32_e32 v252, v144, v145
	v_add_f32_e32 v253, v146, v147
	v_add_f32_e32 v254, v148, v149
	v_add_f32_e32 v255, v150, v151
	v_add_f32_e32 v252, v252, v152
	v_add_f32_e32 v253, v253, v153
	v_add_f32_e32 v254, v254, v154
	v_add_f32_e32 v255, v255, v155
	v_add_f32_e32 v252, v252, v156
	v_add_f32_e32 v253, v253, v157
	v_add_f32_e32 v254, v254, v158
	v_add_f32_e32 v255, v255, v159
	v_cvt_pk_bf16_f32 v6, v144, v145
	v_cvt_pk_bf16_f32 v7, v146, v147
	v_add_f32_e32 v252, v252, v253
	v_add_f32_e32 v254, v254, v255
	v_cvt_pk_bf16_f32 v8, v148, v149
	v_cvt_pk_bf16_f32 v9, v150, v151
	v_cvt_pk_bf16_f32 v208, v152, v153
	v_add_f32_e32 v252, v252, v254
	v_cvt_pk_bf16_f32 v209, v154, v155
	v_cvt_pk_bf16_f32 v210, v156, v157
	v_cvt_pk_bf16_f32 v211, v158, v159
	v_add_u32_e32 v253, 0xde801b54, v252
	v_cmp_gt_u32_e32 vcc, 0x3bff7543, v253
	s_cmp_lg_u64 vcc, exec
	s_cbranch_scc1 .LBB0_444
	v_add_f32_e32 v15, v15, v252
	v_exp_f32_e32 v144, v160
	v_exp_f32_e32 v145, v161
	v_exp_f32_e32 v146, v162
	v_exp_f32_e32 v147, v163
	v_exp_f32_e32 v148, v164
	v_exp_f32_e32 v149, v165
	v_exp_f32_e32 v150, v166
	v_exp_f32_e32 v151, v167
	v_exp_f32_e32 v152, v168
	v_exp_f32_e32 v153, v169
	v_exp_f32_e32 v154, v170
	v_exp_f32_e32 v155, v171
	v_exp_f32_e32 v156, v172
	v_exp_f32_e32 v157, v173
	v_exp_f32_e32 v158, v174
	v_exp_f32_e32 v159, v175
	v_add_f32_e32 v252, v144, v145
	v_add_f32_e32 v253, v146, v147
	v_add_f32_e32 v254, v148, v149
	v_add_f32_e32 v255, v150, v151
	v_add_f32_e32 v252, v252, v152
	v_add_f32_e32 v253, v253, v153
	v_add_f32_e32 v254, v254, v154
	v_add_f32_e32 v255, v255, v155
	v_add_f32_e32 v252, v252, v156
	v_add_f32_e32 v253, v253, v157
	v_add_f32_e32 v254, v254, v158
	v_add_f32_e32 v255, v255, v159
	v_cvt_pk_bf16_f32 v2, v144, v145
	v_cvt_pk_bf16_f32 v3, v146, v147
	v_add_f32_e32 v252, v252, v253
	v_add_f32_e32 v254, v254, v255
	v_cvt_pk_bf16_f32 v4, v148, v149
	v_cvt_pk_bf16_f32 v5, v150, v151
	v_cvt_pk_bf16_f32 v10, v152, v153
	v_add_f32_e32 v252, v252, v254
	v_cvt_pk_bf16_f32 v11, v154, v155
	v_cvt_pk_bf16_f32 v12, v156, v157
	v_cvt_pk_bf16_f32 v13, v158, v159
	v_add_u32_e32 v253, 0xde801b54, v252
	v_cmp_gt_u32_e32 vcc, 0x3bff7543, v253
	s_cmp_lg_u64 vcc, exec
	s_cbranch_scc1 .Lfzsb2_c0
	v_add_f32_e32 v14, v14, v252
	s_branch .LBB0_429

.LBB0_1267:
	v_add_u32_e32 v242, s27, v234
	ds_read_b64_tr_b16 v[160:161], v242 offset:0x0
	ds_read_b64_tr_b16 v[162:163], v242 offset:0x100
	ds_read_b64_tr_b16 v[164:165], v242 offset:0x1000
	ds_read_b64_tr_b16 v[166:167], v242 offset:0x1100
	s_waitcnt lgkmcnt(2)
	v_mfma_f32_32x32x16_bf16 v[128:143], v[216:219], v[160:163], v[128:143]
	ds_read_b64_tr_b16 v[168:169], v242 offset:0x200
	v_mfma_f32_32x32x16_bf16 v[96:111], v[212:215], v[160:163], v[96:111]
	ds_read_b64_tr_b16 v[170:171], v242 offset:0x300
	s_waitcnt lgkmcnt(2)
	v_mfma_f32_32x32x16_bf16 v[128:143], v[224:227], v[164:167], v[128:143]
	ds_read_b64_tr_b16 v[172:173], v242 offset:0x1200
	v_mfma_f32_32x32x16_bf16 v[96:111], v[220:223], v[164:167], v[96:111]
	ds_read_b64_tr_b16 v[174:175], v242 offset:0x1300
	s_waitcnt lgkmcnt(2)
	v_mfma_f32_32x32x16_bf16 v[112:127], v[216:219], v[168:171], v[112:127]
	ds_read_b64_tr_b16 v[160:161], v242 offset:0x400
	v_mfma_f32_32x32x16_bf16 v[80:95], v[212:215], v[168:171], v[80:95]
	ds_read_b64_tr_b16 v[162:163], v242 offset:0x500
	s_waitcnt lgkmcnt(2)
	v_mfma_f32_32x32x16_bf16 v[112:127], v[224:227], v[172:175], v[112:127]
	ds_read_b64_tr_b16 v[164:165], v242 offset:0x1400
	v_mfma_f32_32x32x16_bf16 v[80:95], v[220:223], v[172:175], v[80:95]
	ds_read_b64_tr_b16 v[166:167], v242 offset:0x1500
	ds_read_b128 v[144:147], v241 offset:0x2000
	ds_read_b128 v[148:151], v240 offset:0x2000
	ds_read_b128 v[152:155], v239 offset:0x2000
	ds_read_b128 v[156:159], v0 offset:0x2000
	s_waitcnt lgkmcnt(6)
	v_mfma_f32_32x32x16_bf16 v[64:79], v[216:219], v[160:163], v[64:79]
	ds_read_b64_tr_b16 v[168:169], v242 offset:0x600
	v_mfma_f32_32x32x16_bf16 v[48:63], v[212:215], v[160:163], v[48:63]
	ds_read_b64_tr_b16 v[170:171], v242 offset:0x700
	s_waitcnt lgkmcnt(6)
	v_mfma_f32_32x32x16_bf16 v[64:79], v[224:227], v[164:167], v[64:79]
	ds_read_b64_tr_b16 v[172:173], v242 offset:0x1600
	v_mfma_f32_32x32x16_bf16 v[48:63], v[220:223], v[164:167], v[48:63]
	ds_read_b64_tr_b16 v[174:175], v242 offset:0x1700
	s_waitcnt lgkmcnt(2)
	v_mfma_f32_32x32x16_bf16 v[32:47], v[216:219], v[168:171], v[32:47]
	v_mfma_f32_32x32x16_bf16 v[16:31], v[212:215], v[168:171], v[16:31]
	s_waitcnt lgkmcnt(0)
	v_mfma_f32_32x32x16_bf16 v[32:47], v[224:227], v[172:175], v[32:47]
	v_mfma_f32_32x32x16_bf16 v[16:31], v[220:223], v[172:175], v[16:31]
	s_waitcnt lgkmcnt(0)
	s_barrier
	v_mfma_f32_32x32x16_bf16 v[212:227], v[144:147], v[176:179], 0
	v_mfma_f32_32x32x16_bf16 v[212:227], v[148:151], v[180:183], v[212:227]
	v_mfma_f32_32x32x16_bf16 v[212:227], v[152:155], v[184:187], v[212:227]
	v_mfma_f32_32x32x16_bf16 v[212:227], v[156:159], v[188:191], v[212:227]
	ds_read_b128 v[144:147], v241 offset:0x2080
	ds_read_b128 v[148:151], v240 offset:0x2080
	ds_read_b128 v[152:155], v239 offset:0x2080
	ds_read_b128 v[156:159], v0 offset:0x2080
	v_cmp_eq_f32_e32 vcc, 0, v238
	v_cmp_eq_f32_e64 s[10:11], 0, v237
	s_and_b64 s[0:1], vcc, s[10:11]
	s_cmp_eq_u64 s[0:1], exec
	s_waitcnt lgkmcnt(0)
	v_mfma_f32_32x32x16_bf16 v[160:175], v[144:147], v[192:195], 0
	v_mfma_f32_32x32x16_bf16 v[160:175], v[148:151], v[196:199], v[160:175]
	v_mfma_f32_32x32x16_bf16 v[160:175], v[152:155], v[200:203], v[160:175]
	v_mfma_f32_32x32x16_bf16 v[160:175], v[156:159], v[204:207], v[160:175]
	s_cbranch_scc0 .Lfz2o_c1
	v_exp_f32_e32 v144, v212
	v_exp_f32_e32 v145, v213
	v_exp_f32_e32 v146, v214
	v_exp_f32_e32 v147, v215
	v_exp_f32_e32 v148, v216
	v_exp_f32_e32 v149, v217
	v_exp_f32_e32 v150, v218
	v_exp_f32_e32 v151, v219
	v_exp_f32_e32 v152, v220
	v_exp_f32_e32 v153, v221
	v_exp_f32_e32 v154, v222
	v_exp_f32_e32 v155, v223
	v_exp_f32_e32 v156, v224
	v_exp_f32_e32 v157, v225
	v_exp_f32_e32 v158, v226
	v_exp_f32_e32 v159, v227
	v_add_f32_e32 v252, v144, v145
	v_add_f32_e32 v253, v146, v147
	v_add_f32_e32 v254, v148, v149
	v_add_f32_e32 v255, v150, v151
	v_add_f32_e32 v252, v252, v152
	v_add_f32_e32 v253, v253, v153
	v_add_f32_e32 v254, v254, v154
	v_add_f32_e32 v255, v255, v155
	v_add_f32_e32 v252, v252, v156
	v_add_f32_e32 v253, v253, v157
	v_add_f32_e32 v254, v254, v158
	v_add_f32_e32 v255, v255, v159
	v_cvt_pk_bf16_f32 v6, v144, v145
	v_cvt_pk_bf16_f32 v7, v146, v147
	v_add_f32_e32 v252, v252, v253
	v_add_f32_e32 v254, v254, v255
	v_cvt_pk_bf16_f32 v8, v148, v149
	v_cvt_pk_bf16_f32 v9, v150, v151
	v_cvt_pk_bf16_f32 v208, v152, v153
	v_add_f32_e32 v252, v252, v254
	v_cvt_pk_bf16_f32 v209, v154, v155
	v_cvt_pk_bf16_f32 v210, v156, v157
	v_cvt_pk_bf16_f32 v211, v158, v159
	v_add_u32_e32 v253, 0xde801b54, v252
	v_cmp_gt_u32_e32 vcc, 0x3bff7543, v253
	s_cmp_lg_u64 vcc, exec
	s_cbranch_scc1 .LBB0_1298
	v_add_f32_e32 v15, v15, v252
	v_exp_f32_e32 v144, v160
	v_exp_f32_e32 v145, v161
	v_exp_f32_e32 v146, v162
	v_exp_f32_e32 v147, v163
	v_exp_f32_e32 v148, v164
	v_exp_f32_e32 v149, v165
	v_exp_f32_e32 v150, v166
	v_exp_f32_e32 v151, v167
	v_exp_f32_e32 v152, v168
	v_exp_f32_e32 v153, v169
	v_exp_f32_e32 v154, v170
	v_exp_f32_e32 v155, v171
	v_exp_f32_e32 v156, v172
	v_exp_f32_e32 v157, v173
	v_exp_f32_e32 v158, v174
	v_exp_f32_e32 v159, v175
	v_add_f32_e32 v252, v144, v145
	v_add_f32_e32 v253, v146, v147
	v_add_f32_e32 v254, v148, v149
	v_add_f32_e32 v255, v150, v151
	v_add_f32_e32 v252, v252, v152
	v_add_f32_e32 v253, v253, v153
	v_add_f32_e32 v254, v254, v154
	v_add_f32_e32 v255, v255, v155
	v_add_f32_e32 v252, v252, v156
	v_add_f32_e32 v253, v253, v157
	v_add_f32_e32 v254, v254, v158
	v_add_f32_e32 v255, v255, v159
	v_cvt_pk_bf16_f32 v2, v144, v145
	v_cvt_pk_bf16_f32 v3, v146, v147
	v_add_f32_e32 v252, v252, v253
	v_add_f32_e32 v254, v254, v255
	v_cvt_pk_bf16_f32 v4, v148, v149
	v_cvt_pk_bf16_f32 v5, v150, v151
	v_cvt_pk_bf16_f32 v10, v152, v153
	v_add_f32_e32 v252, v252, v254
	v_cvt_pk_bf16_f32 v11, v154, v155
	v_cvt_pk_bf16_f32 v12, v156, v157
	v_cvt_pk_bf16_f32 v13, v158, v159
	v_add_u32_e32 v253, 0xde801b54, v252
	v_cmp_gt_u32_e32 vcc, 0x3bff7543, v253
	s_cmp_lg_u64 vcc, exec
	s_cbranch_scc1 .Lfzsb2_c1
	v_add_f32_e32 v14, v14, v252
	s_branch .LBB0_1283

.LBB0_2121:
	v_add_u32_e32 v242, s27, v234
	ds_read_b64_tr_b16 v[160:161], v242 offset:0x0
	ds_read_b64_tr_b16 v[162:163], v242 offset:0x100
	ds_read_b64_tr_b16 v[164:165], v242 offset:0x1000
	ds_read_b64_tr_b16 v[166:167], v242 offset:0x1100
	s_waitcnt lgkmcnt(2)
	v_mfma_f32_32x32x16_bf16 v[128:143], v[216:219], v[160:163], v[128:143]
	ds_read_b64_tr_b16 v[168:169], v242 offset:0x200
	v_mfma_f32_32x32x16_bf16 v[96:111], v[212:215], v[160:163], v[96:111]
	ds_read_b64_tr_b16 v[170:171], v242 offset:0x300
	s_waitcnt lgkmcnt(2)
	v_mfma_f32_32x32x16_bf16 v[128:143], v[224:227], v[164:167], v[128:143]
	ds_read_b64_tr_b16 v[172:173], v242 offset:0x1200
	v_mfma_f32_32x32x16_bf16 v[96:111], v[220:223], v[164:167], v[96:111]
	ds_read_b64_tr_b16 v[174:175], v242 offset:0x1300
	s_waitcnt lgkmcnt(2)
	v_mfma_f32_32x32x16_bf16 v[112:127], v[216:219], v[168:171], v[112:127]
	ds_read_b64_tr_b16 v[160:161], v242 offset:0x400
	v_mfma_f32_32x32x16_bf16 v[80:95], v[212:215], v[168:171], v[80:95]
	ds_read_b64_tr_b16 v[162:163], v242 offset:0x500
	s_waitcnt lgkmcnt(2)
	v_mfma_f32_32x32x16_bf16 v[112:127], v[224:227], v[172:175], v[112:127]
	ds_read_b64_tr_b16 v[164:165], v242 offset:0x1400
	v_mfma_f32_32x32x16_bf16 v[80:95], v[220:223], v[172:175], v[80:95]
	ds_read_b64_tr_b16 v[166:167], v242 offset:0x1500
	ds_read_b128 v[144:147], v241 offset:0x2000
	ds_read_b128 v[148:151], v240 offset:0x2000
	ds_read_b128 v[156:159], v239 offset:0x2000
	ds_read_b128 v[244:247], v0 offset:0x2000
	s_waitcnt lgkmcnt(6)
	v_mfma_f32_32x32x16_bf16 v[64:79], v[216:219], v[160:163], v[64:79]
	ds_read_b64_tr_b16 v[168:169], v242 offset:0x600
	v_mfma_f32_32x32x16_bf16 v[32:47], v[212:215], v[160:163], v[32:47]
	ds_read_b64_tr_b16 v[170:171], v242 offset:0x700
	s_waitcnt lgkmcnt(6)
	v_mfma_f32_32x32x16_bf16 v[64:79], v[224:227], v[164:167], v[64:79]
	ds_read_b64_tr_b16 v[172:173], v242 offset:0x1600
	v_mfma_f32_32x32x16_bf16 v[32:47], v[220:223], v[164:167], v[32:47]
	ds_read_b64_tr_b16 v[174:175], v242 offset:0x1700
	s_waitcnt lgkmcnt(2)
	v_mfma_f32_32x32x16_bf16 v[48:63], v[216:219], v[168:171], v[48:63]
	v_mfma_f32_32x32x16_bf16 v[16:31], v[212:215], v[168:171], v[16:31]
	s_waitcnt lgkmcnt(0)
	v_mfma_f32_32x32x16_bf16 v[48:63], v[224:227], v[172:175], v[48:63]
	v_mfma_f32_32x32x16_bf16 v[16:31], v[220:223], v[172:175], v[16:31]
	s_waitcnt lgkmcnt(0)
	s_barrier
	v_mfma_f32_32x32x16_bf16 v[212:227], v[144:147], v[176:179], 0
	v_mfma_f32_32x32x16_bf16 v[212:227], v[148:151], v[180:183], v[212:227]
	v_mfma_f32_32x32x16_bf16 v[212:227], v[156:159], v[184:187], v[212:227]
	v_mfma_f32_32x32x16_bf16 v[212:227], v[244:247], v[188:191], v[212:227]
	ds_read_b128 v[144:147], v241 offset:0x2080
	ds_read_b128 v[148:151], v240 offset:0x2080
	ds_read_b128 v[152:155], v239 offset:0x2080
	ds_read_b128 v[156:159], v0 offset:0x2080
	v_cmp_eq_f32_e32 vcc, 0, v238
	v_cmp_eq_f32_e64 s[6:7], 0, v237
	s_and_b64 s[0:1], vcc, s[6:7]
	s_cmp_eq_u64 s[0:1], exec
	s_waitcnt lgkmcnt(0)
	v_mfma_f32_32x32x16_bf16 v[160:175], v[144:147], v[192:195], 0
	v_mfma_f32_32x32x16_bf16 v[160:175], v[148:151], v[196:199], v[160:175]
	v_mfma_f32_32x32x16_bf16 v[160:175], v[152:155], v[200:203], v[160:175]
	v_mfma_f32_32x32x16_bf16 v[160:175], v[156:159], v[204:207], v[160:175]
	s_cbranch_scc0 .Lfz2o_c2
	v_exp_f32_e32 v144, v212
	v_exp_f32_e32 v145, v213
	v_exp_f32_e32 v146, v214
	v_exp_f32_e32 v147, v215
	v_exp_f32_e32 v148, v216
	v_exp_f32_e32 v149, v217
	v_exp_f32_e32 v150, v218
	v_exp_f32_e32 v151, v219
	v_exp_f32_e32 v152, v220
	v_exp_f32_e32 v153, v221
	v_exp_f32_e32 v154, v222
	v_exp_f32_e32 v155, v223
	v_exp_f32_e32 v156, v224
	v_exp_f32_e32 v157, v225
	v_exp_f32_e32 v158, v226
	v_exp_f32_e32 v159, v227
	v_add_f32_e32 v252, v144, v145
	v_add_f32_e32 v253, v146, v147
	v_add_f32_e32 v254, v148, v149
	v_add_f32_e32 v255, v150, v151
	v_add_f32_e32 v252, v252, v152
	v_add_f32_e32 v253, v253, v153
	v_add_f32_e32 v254, v254, v154
	v_add_f32_e32 v255, v255, v155
	v_add_f32_e32 v252, v252, v156
	v_add_f32_e32 v253, v253, v157
	v_add_f32_e32 v254, v254, v158
	v_add_f32_e32 v255, v255, v159
	v_cvt_pk_bf16_f32 v6, v144, v145
	v_cvt_pk_bf16_f32 v7, v146, v147
	v_add_f32_e32 v252, v252, v253
	v_add_f32_e32 v254, v254, v255
	v_cvt_pk_bf16_f32 v8, v148, v149
	v_cvt_pk_bf16_f32 v9, v150, v151
	v_cvt_pk_bf16_f32 v208, v152, v153
	v_add_f32_e32 v252, v252, v254
	v_cvt_pk_bf16_f32 v209, v154, v155
	v_cvt_pk_bf16_f32 v210, v156, v157
	v_cvt_pk_bf16_f32 v211, v158, v159
	v_add_u32_e32 v253, 0xde801b54, v252
	v_cmp_gt_u32_e32 vcc, 0x3bff7543, v253
	s_cmp_lg_u64 vcc, exec
	s_cbranch_scc1 .LBB0_2152
	v_add_f32_e32 v15, v15, v252
	v_exp_f32_e32 v144, v160
	v_exp_f32_e32 v145, v161
	v_exp_f32_e32 v146, v162
	v_exp_f32_e32 v147, v163
	v_exp_f32_e32 v148, v164
	v_exp_f32_e32 v149, v165
	v_exp_f32_e32 v150, v166
	v_exp_f32_e32 v151, v167
	v_exp_f32_e32 v152, v168
	v_exp_f32_e32 v153, v169
	v_exp_f32_e32 v154, v170
	v_exp_f32_e32 v155, v171
	v_exp_f32_e32 v156, v172
	v_exp_f32_e32 v157, v173
	v_exp_f32_e32 v158, v174
	v_exp_f32_e32 v159, v175
	v_add_f32_e32 v252, v144, v145
	v_add_f32_e32 v253, v146, v147
	v_add_f32_e32 v254, v148, v149
	v_add_f32_e32 v255, v150, v151
	v_add_f32_e32 v252, v252, v152
	v_add_f32_e32 v253, v253, v153
	v_add_f32_e32 v254, v254, v154
	v_add_f32_e32 v255, v255, v155
	v_add_f32_e32 v252, v252, v156
	v_add_f32_e32 v253, v253, v157
	v_add_f32_e32 v254, v254, v158
	v_add_f32_e32 v255, v255, v159
	v_cvt_pk_bf16_f32 v2, v144, v145
	v_cvt_pk_bf16_f32 v3, v146, v147
	v_add_f32_e32 v252, v252, v253
	v_add_f32_e32 v254, v254, v255
	v_cvt_pk_bf16_f32 v4, v148, v149
	v_cvt_pk_bf16_f32 v5, v150, v151
	v_cvt_pk_bf16_f32 v10, v152, v153
	v_add_f32_e32 v252, v252, v254
	v_cvt_pk_bf16_f32 v11, v154, v155
	v_cvt_pk_bf16_f32 v12, v156, v157
	v_cvt_pk_bf16_f32 v13, v158, v159
	v_add_u32_e32 v253, 0xde801b54, v252
	v_cmp_gt_u32_e32 vcc, 0x3bff7543, v253
	s_cmp_lg_u64 vcc, exec
	s_cbranch_scc1 .Lfzsb2_c2
	v_add_f32_e32 v14, v14, v252
	s_branch .LBB0_2137
